# scan items assigned to the XCD that owns the span's row block (grid 256); XCD leader also skips buffer_wbl2 after hgrn in-proj and after scan pass C
# speedup vs baseline: 1.0319x; 1.0048x over previous
_Z8yoco_fwd1P:
	s_mov_b64 s[52:53], s[0:1]
	s_load_dwordx2 s[72:73], s[0:1], 0xe0
	s_add_u32 s0, s52, 0xe0
	v_writelane_b32 v253, s2, 0
	s_addc_u32 s1, s53, 0
	v_writelane_b32 v253, s0, 1
	v_and_b32_e32 v220, 0x3ff, v0
	v_cmp_gt_u32_e32 vcc, 4, v220
	v_writelane_b32 v253, s1, 2
	s_and_saveexec_b64 s[0:1], vcc
	v_lshl_add_u32 v1, v220, 2, 0
	v_add_u32_e32 v1, 0x20000, v1
	v_mov_b32_e32 v2, 0
	ds_write_b32 v1, v2
	s_or_b64 exec, exec, s[0:1]
	s_waitcnt lgkmcnt(0)
	s_barrier
	s_load_dword s1, s[52:53], 0xe8
	s_mul_i32 s0, s73, s72
	v_readlane_b32 s5, v253, 0
	s_mov_b32 s95, 0
	s_movk_i32 s70, 0x1000
	s_waitcnt lgkmcnt(0)
	s_mul_i32 s51, s0, s1
	v_sub_co_u32_e64 v1, s[0:1], s5, 42
	s_nop 0
	v_readfirstlane_b32 s2, v1
	s_lshr_b32 s2, s2, 4
	s_add_i32 s2, s2, 5
	s_and_b64 s[0:1], s[0:1], exec
	s_cselect_b32 s0, 4, s2
	s_cmp_gt_u32 s5, 39
	s_cselect_b32 s0, s0, 3
	s_cmp_gt_u32 s5, 35
	s_cselect_b32 s2, s0, 2
	s_not_b32 s0, s5
	s_add_i32 s0, s72, s0
	v_writelane_b32 v253, s0, 3
	s_lshl_b32 s0, s5, 9
	v_writelane_b32 v253, s0, 4
	s_lshl_b32 s66, s72, 9
	s_lshl_b32 s0, s5, 1
	s_cmp_lg_u32 s72, 0x100
	s_cbranch_scc1 .Lit_keep
	s_and_b32 s98, s5, 7
	s_lshr_b32 s99, s5, 3
	s_lshr_b32 s0, s98, 1
	s_lshl_b32 s0, s0, 3
	s_lshr_b32 s100, s99, 2
	s_add_i32 s0, s0, s100
	s_lshl_b32 s0, s0, 4
	s_and_b32 s100, s98, 1
	s_lshl_b32 s100, s100, 3
	s_add_i32 s0, s0, s100
	s_and_b32 s100, s99, 3
	s_lshl_b32 s100, s100, 1
	s_add_i32 s0, s0, s100
.Lit_keep:
	s_cmpk_lt_i32 s0, 0x200
	v_writelane_b32 v253, s0, 5
	s_cselect_b64 s[0:1], -1, 0
	s_lshl_b32 s68, s72, 1
	v_writelane_b32 v253, s0, 6
	s_cmpk_lt_i32 s5, 0x200
	v_lshrrev_b32_e32 v1, 20, v0
	v_writelane_b32 v253, s1, 7
	s_cselect_b64 s[0:1], -1, 0
	v_writelane_b32 v253, s0, 8
	v_lshrrev_b32_e32 v0, 10, v0
	v_or_b32_e32 v0, v0, v1
	v_writelane_b32 v253, s1, 9
	s_add_i32 s0, s5, 0x200
	s_cmpk_lt_i32 s0, 0x400
	v_writelane_b32 v253, s0, 10
	s_cselect_b64 s[0:1], -1, 0
	v_writelane_b32 v253, s0, 11
	v_cvt_f32_u32_e32 v2, s66
	s_mov_b32 s67, s66
	v_writelane_b32 v253, s1, 12
	s_and_b32 s0, s5, 1
	s_cmp_eq_u32 s0, 0
	s_cselect_b64 s[6:7], -1, 0
	v_writelane_b32 v253, s6, 13
	s_cmp_eq_u32 s0, 1
	s_cselect_b64 s[0:1], -1, 0
	v_writelane_b32 v253, s7, 14
	v_writelane_b32 v253, s0, 15
	s_cmpk_lt_i32 s5, 0x400
	v_rcp_iflag_f32_e32 v2, v2
	v_writelane_b32 v253, s1, 16
	s_cselect_b64 s[0:1], -1, 0
	v_writelane_b32 v253, s0, 17
	v_mov_b32_e32 v193, 0
	s_mov_b32 s54, -2
	v_writelane_b32 v253, s1, 18
	s_ashr_i32 s0, s5, 3
	s_ashr_i32 s1, s0, 31
	s_lshl_b64 s[0:1], s[0:1], 10
	s_add_u32 s0, s0, 0x1000000
	s_addc_u32 s1, s1, 0
	s_lshl_b32 s3, s5, 7
	s_and_b32 s4, s3, 0x380
	s_add_i32 s3, s72, s5
	s_or_b32 s6, s0, s4
	s_mov_b32 s7, s1
	s_lshl_b32 s69, s72, 3
	s_lshl_b32 s3, s3, 3
	v_writelane_b32 v253, s6, 19
	s_cmp_gt_u32 s5, 31
	s_cselect_b32 s2, s2, 1
	v_writelane_b32 v253, s7, 20
	s_cmp_gt_i32 s5, 15
	v_writelane_b32 v253, s3, 21
	s_movk_i32 s3, 0x3ff
	s_cselect_b32 s6, s2, 0
	v_and_or_b32 v0, v0, s3, v220
	s_lshl_b32 s3, s6, 4
	s_sub_i32 s3, s3, 38
	s_cmp_gt_i32 s5, 31
	v_writelane_b32 v253, s3, 22
	s_cselect_b64 s[8:9], -1, 0
	v_writelane_b32 v253, s8, 23
	s_cmp_gt_u32 s2, 3
	s_mov_b32 s7, s95
	v_writelane_b32 v253, s9, 24
	s_cselect_b64 s[8:9], -1, 0
	v_writelane_b32 v253, s8, 25
	s_cmp_lg_u32 s2, 4
	s_mov_b32 s71, 0x20000
	v_writelane_b32 v253, s9, 26
	s_cselect_b64 s[8:9], -1, 0
	v_writelane_b32 v253, s8, 27
	s_add_i32 s94, s2, -5
	s_mov_b32 s73, 0x1ffff
	v_writelane_b32 v253, s9, 28
	s_lshl_b64 s[8:9], s[94:95], 23
	v_writelane_b32 v253, s8, 29
	s_add_i32 s94, s2, -2
	s_lshl_b64 s[2:3], s[94:95], 21
	v_writelane_b32 v253, s9, 30
	v_writelane_b32 v253, s2, 31
	s_mov_b32 s8, s6
	s_mov_b32 s87, 0x800000
	v_writelane_b32 v253, s3, 32
	s_lshl_b32 s2, s6, 23
	v_writelane_b32 v253, s2, 33
	s_lshl_b64 s[2:3], s[6:7], 19
	v_writelane_b32 v253, s2, 34
	v_mov_b32_e32 v252, 0x1000
	v_mov_b32_e32 v234, 0x2000
	v_writelane_b32 v253, s3, 35
	s_lshl_b32 s2, s6, 12
	s_addk_i32 s2, 0xda00
	s_mul_hi_i32 s3, s2, 0x210
	s_mulk_i32 s2, 0x210
	v_writelane_b32 v253, s2, 36
	v_mov_b32_e32 v227, 1
	v_mov_b32_e32 v226, 0x358637bd
	v_writelane_b32 v253, s3, 37
	s_and_b32 s2, s6, 0xffffffe
	s_cmp_eq_u32 s6, 4
	s_cselect_b32 s3, 0x200, s70
	s_cmp_lg_u32 s2, 2
	s_cselect_b32 s2, s3, 0x400
	s_abs_i32 s6, s69
	v_cvt_f32_u32_e32 v1, s6
	v_writelane_b32 v253, s8, 38
	s_mov_b32 s3, -1
	s_lshl_b32 s57, s72, 6
	v_rcp_iflag_f32_e32 v1, v1
	v_writelane_b32 v253, s9, 39
	v_writelane_b32 v253, s2, 40
	s_mov_b32 s2, s95
	v_mul_f32_e32 v1, 0x4f7ffffe, v1
	v_cvt_u32_f32_e32 v1, v1
	s_and_b64 s[2:3], s[66:67], s[2:3]
	v_writelane_b32 v253, s2, 41
	s_lshl_b32 s58, s72, 5
	s_lshl_b64 s[0:1], s[0:1], 1
	v_writelane_b32 v253, s3, 42
	s_sub_i32 s2, 0, s6
	v_readfirstlane_b32 s3, v1
	v_mul_f32_e32 v1, 0x4f7ffffe, v2
	s_mul_i32 s2, s2, s3
	v_cvt_u32_f32_e32 v1, v1
	s_mul_hi_u32 s2, s3, s2
	v_writelane_b32 v253, s6, 43
	s_add_i32 s2, s3, s2
	v_writelane_b32 v253, s2, 44
	s_sub_i32 s2, 0, s66
	v_mul_lo_u32 v2, s2, v1
	s_lshl_b32 s2, s5, 6
	s_sub_i32 s2, s57, s2
	s_addk_i32 s2, 0x3fc0
	v_writelane_b32 v253, s2, 45
	s_lshl_b32 s2, s5, 5
	s_sub_i32 s2, s58, s2
	s_addk_i32 s2, 0x3fe0
	v_writelane_b32 v253, s2, 46
	s_lshl_b32 s2, s5, 10
	v_writelane_b32 v253, s2, 47
	s_lshl_b32 s2, s4, 1
	v_writelane_b32 v253, s2, 48
	v_writelane_b32 v253, s0, 49
	s_lshl_b32 s55, s72, 10
	s_mov_b32 s56, s55
	v_writelane_b32 v253, s1, 50
	s_add_i32 s0, 0, 0x20004
	v_writelane_b32 v253, s0, 51
	s_add_i32 s0, 0, 0x10800
	v_writelane_b32 v253, s0, 52
	s_add_i32 s0, 0, 0x11400
	v_writelane_b32 v253, s0, 53
	s_add_i32 s0, 0, 0x11420
	v_writelane_b32 v253, s0, 54
	s_add_i32 s0, 0, 0x10c00
	v_writelane_b32 v253, s0, 55
	s_add_i32 s0, 0, 0x11440
	v_writelane_b32 v253, s0, 56
	v_cmp_eq_u32_e64 s[0:1], 0, v220
	v_mul_hi_u32 v2, v1, v2
	s_ashr_i32 s67, s66, 31
	v_writelane_b32 v253, s0, 57
	v_add_u32_e32 v221, v1, v2
	s_lshl_b64 s[60:61], s[66:67], 2
	v_writelane_b32 v253, s1, 58
	v_cmp_eq_u32_e64 s[0:1], 0, v0
	v_mbcnt_lo_u32_b32 v1, -1, 0
	v_mov_b32_e32 v228, 0x46000000
	v_writelane_b32 v253, s0, 59
	v_not_b32_e32 v229, 63
	v_not_b32_e32 v230, 31
	v_writelane_b32 v253, s1, 60
	v_writelane_b32 v253, s52, 61
	s_mov_b32 s0, s72
	v_mov_b32_e32 v231, 0x7fc00000
	v_writelane_b32 v253, s53, 62
	v_writelane_b32 v253, s0, 63
	v_mov_b32_e32 v222, v193
	v_mov_b32_e32 v223, v193
	v_writelane_b32 v254, s1, 0
	s_mov_b32 s0, s66
	v_writelane_b32 v254, s0, 1
	v_mov_b32_e32 v224, v193
	v_mov_b32_e32 v225, v193
	v_writelane_b32 v254, s1, 2
	v_writelane_b32 v254, s68, 3
	v_writelane_b32 v254, s69, 4
	v_writelane_b32 v254, s51, 5
	v_writelane_b32 v254, s55, 6
	v_writelane_b32 v254, s56, 7
	v_writelane_b32 v254, s57, 8
	v_writelane_b32 v254, s58, 9
	v_writelane_b32 v254, s60, 10
	v_mbcnt_hi_u32_b32 v232, -1, v1
	v_mov_b32_e32 v233, 0xf149f2ca
	v_mov_b32_e32 v235, 0x4000
	v_mov_b32_e32 v236, 0x8000
	v_mov_b32_e32 v237, 0xc000
	v_mov_b32_e32 v238, 0x1a000
	s_mov_b32 s74, 0x50000
	s_mov_b32 s75, 0xe000
	s_movk_i32 s33, 0x2000
	s_movk_i32 s78, 0x3000
	s_movk_i32 s5, 0x4000
	s_movk_i32 s79, 0x5000
	s_movk_i32 s88, 0x6000
	s_movk_i32 s80, 0x7000
	s_mov_b32 s81, 0x8000
	s_mov_b32 s59, 0xa000
	s_mov_b32 s64, 0xf000
	s_movk_i32 s89, 0x90
	s_mov_b32 s67, 0xc000
	s_mov_b32 s4, 0x3e38aa3b
	s_mov_b64 s[90:91], 0x80
	s_mov_b64 s[96:97], 0x100
	v_writelane_b32 v254, s61, 11
	s_branch .LBB0_4

.LBB0_1202:
	s_andn2_saveexec_b64 s[8:9], s[8:9]
	s_cbranch_execz .LBB0_1222
	s_mov_b64 s[8:9], exec
	s_cmp_lt_i32 s54, 1
	s_cbranch_scc1 .Lxb_wb
	s_movk_i32 s101, 0xd0
	s_cmp_lt_i32 s54, 16
	s_cselect_b32 s101, 0xda, s101
	s_and_b32 s100, s54, 7
	s_lshr_b32 s100, s101, s100
	s_bitcmp1_b32 s100, 0
	s_cbranch_scc0 .Lxb_wb
	v_mov_b32_e32 v20, 0x20008
	ds_read_b32 v20, v20
	s_waitcnt lgkmcnt(0)
	v_readfirstlane_b32 s100, v20
	s_nop 0
	s_cmp_eq_u32 s100, 1
	s_cbranch_scc1 .Lxb_nowb
